# v51 + MLA loop: all lgkmcnt waits of both halves re-derived per consumer (QK pairs wait (1)/(0), loop top (3..0))
# speedup vs baseline: 1.0028x; 1.0028x over previous
.LBB0_543:
	s_mov_b32 s23, s17
	s_mov_b32 s17, s0
	s_add_i32 s71, 0, 0x10000
	ds_read_b128 v[66:69], v174 offset:49152
	ds_read_b128 v[70:73], v174 offset:57344
	ds_read_b128 v[206:209], v176 offset:49152
	ds_read_b128 v[210:213], v176 offset:57344
	v_fma_f32 v152, v74, s34, v146
	v_fma_f32 v153, v75, s34, v146
	v_fma_f32 v150, v76, s34, v146
	v_fma_f32 v151, v77, s34, v146
	v_fma_f32 v148, v78, s34, v146
	v_fma_f32 v149, v79, s34, v146
	v_fma_f32 v147, v81, s34, v146
	v_fma_f32 v146, v80, s34, v146
	v_exp_f32_e32 v229, v229
	v_exp_f32_e32 v231, v231
	v_exp_f32_e32 v227, v227
	v_exp_f32_e32 v230, v230
	v_exp_f32_e32 v226, v226
	v_exp_f32_e32 v228, v228
	s_waitcnt lgkmcnt(3)
	v_mfma_f32_32x32x16_bf16 v[82:97], v[66:69], v[142:145], 0
	s_add_i32 s0, 0, 0x16000
	v_exp_f32_e32 v240, v146
	v_add_f32_e32 v146, 0, v229
	v_add_f32_e32 v146, v231, v146
	v_add_f32_e32 v146, v227, v146
	v_add_f32_e32 v146, v230, v146
	v_add_f32_e32 v146, v226, v146
	v_exp_f32_e32 v224, v224
	v_exp_f32_e32 v225, v225
	v_exp_f32_e32 v221, v221
	v_exp_f32_e32 v223, v223
	s_waitcnt lgkmcnt(2)
	v_mfma_f32_32x32x16_bf16 v[66:81], v[70:73], v[142:145], 0
	v_exp_f32_e32 v220, v220
	v_exp_f32_e32 v222, v222
	v_add_f32_e32 v146, v228, v146
	v_add_f32_e32 v146, v224, v146
	v_add_f32_e32 v146, v225, v146
	v_add_f32_e32 v146, v221, v146
	v_add_f32_e32 v146, v223, v146
	v_add_f32_e32 v146, v220, v146
	v_add_f32_e32 v146, v222, v146
	v_exp_f32_e32 v217, v217
	v_exp_f32_e32 v219, v219
	v_exp_f32_e32 v216, v216
	v_exp_f32_e32 v218, v218
	s_waitcnt lgkmcnt(1)
	v_mfma_f32_32x32x16_bf16 v[82:97], v[206:209], v[138:141], v[82:97]
	v_exp_f32_e32 v164, v164
	v_add_f32_e32 v146, v217, v146
	v_exp_f32_e32 v165, v165
	v_add_f32_e32 v146, v219, v146
	v_exp_f32_e32 v197, v162
	v_add_f32_e32 v146, v216, v146
	v_add_f32_e32 v146, v218, v146
	s_waitcnt lgkmcnt(0)
	v_mfma_f32_32x32x16_bf16 v[66:81], v[210:213], v[138:141], v[66:81]
	ds_read_b128 v[206:209], v178 offset:49152
	ds_read_b128 v[210:213], v178 offset:57344
	s_add_u32 s4, s38, s20
	s_addc_u32 s5, s39, s21
	s_add_u32 s24, s4, 0x149ec400
	s_addc_u32 s25, s5, 0
	s_mov_b32 m0, s90
	v_lshl_add_u64 v[254:255], v[246:247], 0, s[24:25]
	s_lshl_b32 s18, s22, 14
	global_load_lds_dwordx4 v[254:255], off
	s_add_u32 s24, s4, 0x14a0c400
	s_addc_u32 s25, s5, 0
	s_mov_b32 m0, s91
	v_lshl_add_u64 v[254:255], v[246:247], 0, s[24:25]
	s_add_i32 s1, s89, s18
	global_load_lds_dwordx4 v[254:255], off
	s_add_u32 s24, s4, 0x149ec500
	s_addc_u32 s25, s5, 0
	s_mov_b32 m0, s1
	v_lshl_add_u64 v[254:255], v[248:249], 0, s[24:25]
	global_load_lds_dwordx4 v[254:255], off
	s_add_u32 s24, s4, 0x14a0c500
	s_addc_u32 s25, s5, 0
	s_add_i32 m0, s1, 0x2000
	v_lshl_add_u64 v[254:255], v[248:249], 0, s[24:25]
	global_load_lds_dwordx4 v[254:255], off
	s_add_u32 s4, s38, s88
	s_addc_u32 s5, s39, s87
	s_add_u32 s4, s4, s36
	s_addc_u32 s5, s5, s37
	s_mov_b32 m0, s92
	v_lshl_add_u64 v[254:255], v[250:251], 0, s[4:5]
	global_load_lds_dwordx4 v[254:255], off
	v_exp_f32_e32 v156, v156
	v_add_f32_e32 v146, v164, v146
	v_exp_f32_e32 v157, v157
	v_add_f32_e32 v146, v165, v146
	v_add_f32_e32 v146, v197, v146
	v_exp_f32_e32 v241, v147
	s_waitcnt lgkmcnt(1)
	v_mfma_f32_32x32x16_bf16 v[82:97], v[206:209], v[134:137], v[82:97]
	s_waitcnt lgkmcnt(0)
	v_mfma_f32_32x32x16_bf16 v[66:81], v[210:213], v[134:137], v[66:81]
	ds_read_b128 v[208:211], v180 offset:49152
	ds_read_b128 v[212:215], v180 offset:57344
	s_waitcnt lgkmcnt(1)
	v_mfma_f32_32x32x16_bf16 v[82:97], v[208:211], v[130:133], v[82:97]
	s_waitcnt lgkmcnt(0)
	v_mfma_f32_32x32x16_bf16 v[66:81], v[212:215], v[130:133], v[66:81]
	ds_read_b128 v[208:211], v182 offset:49152
	ds_read_b128 v[212:215], v182 offset:57344
	s_waitcnt lgkmcnt(1)
	v_mfma_f32_32x32x16_bf16 v[82:97], v[208:211], v[126:129], v[82:97]
	s_waitcnt lgkmcnt(0)
	v_mfma_f32_32x32x16_bf16 v[66:81], v[212:215], v[126:129], v[66:81]
	ds_read_b128 v[210:213], v186 offset:49152
	ds_read_b128 v[232:235], v186 offset:57344
	s_waitcnt lgkmcnt(1)
	v_mfma_f32_32x32x16_bf16 v[82:97], v[210:213], v[122:125], v[82:97]
	s_waitcnt lgkmcnt(0)
	v_mfma_f32_32x32x16_bf16 v[66:81], v[232:235], v[122:125], v[66:81]
	ds_read_b128 v[210:213], v188 offset:49152
	ds_read_b128 v[232:235], v188 offset:57344
	s_waitcnt lgkmcnt(1)
	v_mfma_f32_32x32x16_bf16 v[82:97], v[210:213], v[118:121], v[82:97]
	s_waitcnt lgkmcnt(0)
	v_mfma_f32_32x32x16_bf16 v[66:81], v[232:235], v[118:121], v[66:81]
	ds_read_b128 v[212:215], v190 offset:49152
	ds_read_b128 v[232:235], v190 offset:57344
	s_waitcnt lgkmcnt(1)
	v_mfma_f32_32x32x16_bf16 v[82:97], v[212:215], v[114:117], v[82:97]
	s_waitcnt lgkmcnt(0)
	v_mfma_f32_32x32x16_bf16 v[66:81], v[232:235], v[114:117], v[66:81]
	ds_read_b128 v[212:215], v192 offset:8192
	ds_read_b128 v[232:235], v192 offset:12288
	s_waitcnt lgkmcnt(1)
	v_mfma_f32_32x32x16_bf16 v[82:97], v[212:215], v[110:113], v[82:97]
	v_exp_f32_e32 v215, v163
	s_nop 0
	v_add_f32_e32 v146, v215, v146
	s_waitcnt lgkmcnt(0)
	v_mfma_f32_32x32x16_bf16 v[66:81], v[232:235], v[110:113], v[66:81]
	s_lshl_b32 s24, s17, 14
	v_add_u32_e32 v245, s24, v200
	ds_read_b64_tr_b16 v[206:207], v245 offset:0
	ds_read_b64_tr_b16 v[208:209], v245 offset:0x800
	ds_read_b64_tr_b16 v[210:211], v245 offset:0x1000
	ds_read_b64_tr_b16 v[212:213], v245 offset:0x1800
	ds_read_b128 v[232:235], v194 offset:8192
	ds_read_b128 v[236:239], v194 offset:12288
	v_add_f32_e32 v146, v156, v146
	v_add_f32_e32 v146, v157, v146
	s_waitcnt lgkmcnt(1)
	v_mfma_f32_32x32x16_bf16 v[82:97], v[232:235], v[106:109], v[82:97]
	s_waitcnt lgkmcnt(0)
	v_mfma_f32_32x32x16_bf16 v[66:81], v[236:239], v[106:109], v[66:81]
	ds_read_b128 v[232:235], v196 offset:8192
	ds_read_b128 v[236:239], v196 offset:12288
	s_waitcnt lgkmcnt(1)
	v_mfma_f32_32x32x16_bf16 v[82:97], v[232:235], v[102:105], v[82:97]
	s_waitcnt lgkmcnt(0)
	v_mfma_f32_32x32x16_bf16 v[66:81], v[236:239], v[102:105], v[66:81]
	ds_read_b128 v[232:235], v199 offset:8192
	ds_read_b128 v[236:239], v199 offset:12288
	s_waitcnt lgkmcnt(1)
	v_mfma_f32_32x32x16_bf16 v[82:97], v[232:235], v[98:101], v[82:97]
	v_exp_f32_e32 v232, v154
	v_exp_f32_e32 v233, v155
	v_exp_f32_e32 v234, v152
	v_exp_f32_e32 v235, v153
	v_add_f32_e32 v146, v232, v146
	v_add_f32_e32 v146, v233, v146
	v_add_f32_e32 v146, v234, v146
	s_waitcnt lgkmcnt(0)
	v_mfma_f32_32x32x16_bf16 v[66:81], v[236:239], v[98:101], v[66:81]
	v_exp_f32_e32 v236, v150
	v_exp_f32_e32 v237, v151
	v_exp_f32_e32 v238, v148
	v_exp_f32_e32 v239, v149
	v_add_f32_e32 v146, v235, v146
	v_add_f32_e32 v146, v236, v146
	v_add_f32_e32 v146, v237, v146
	v_add_f32_e32 v146, v238, v146
	v_add_f32_e32 v146, v239, v146
	v_add_f32_e32 v146, v240, v146
	v_add_f32_e32 v162, v241, v146
	v_mov_b32_e32 v163, v162
	s_nop 1
	v_permlane32_swap_b32_e32 v162, v163
	v_cvt_pk_bf16_f32 v146, v229, v231
	v_cvt_pk_bf16_f32 v147, v227, v230
	v_cvt_pk_bf16_f32 v148, v226, v228
	v_cvt_pk_bf16_f32 v149, v224, v225
	v_cvt_pk_bf16_f32 v150, v221, v223
	v_cvt_pk_bf16_f32 v151, v220, v222
	v_cvt_pk_bf16_f32 v152, v217, v219
	v_cvt_pk_bf16_f32 v153, v216, v218
	v_cvt_pk_bf16_f32 v154, v164, v165
	v_cvt_pk_bf16_f32 v155, v197, v215
	v_cvt_pk_bf16_f32 v156, v156, v157
	v_cvt_pk_bf16_f32 v157, v232, v233
	v_cvt_pk_bf16_f32 v216, v234, v235
	v_cvt_pk_bf16_f32 v217, v236, v237
	v_cvt_pk_bf16_f32 v218, v238, v239
	v_cvt_pk_bf16_f32 v219, v240, v241
	s_nop 0
	v_permlane32_swap_b32_e32 v146, v148
	v_permlane32_swap_b32_e32 v147, v149
	v_permlane32_swap_b32_e32 v150, v152
	v_permlane32_swap_b32_e32 v151, v153
	v_permlane32_swap_b32_e32 v154, v156
	v_permlane32_swap_b32_e32 v155, v157
	v_permlane32_swap_b32_e32 v216, v218
	v_permlane32_swap_b32_e32 v217, v219
	s_lshl_b32 s24, s17, 14
	v_add_u32_e32 v197, s24, v200
	ds_read_b64_tr_b16 v[228:229], v197 offset:0x2000
	ds_read_b64_tr_b16 v[230:231], v197 offset:0x2800
	ds_read_b64_tr_b16 v[232:233], v197 offset:0x3000
	ds_read_b64_tr_b16 v[234:235], v197 offset:0x3800
	s_nop 0
	v_mfma_f32_32x32x16_bf16 v[2:17], v[146:149], v[206:209], v[2:17]
	ds_read_b64_tr_b16 v[220:221], v197 offset:0x200
	ds_read_b64_tr_b16 v[222:223], v197 offset:0xa00
	v_max_f32_e32 v164, v83, v83
	v_max_f32_e32 v165, v82, v82
	v_max_f32_e32 v164, v165, v164
	v_max3_f32 v164, v164, v84, v85
	v_max3_f32 v164, v164, v86, v87
	v_mfma_f32_32x32x16_bf16 v[2:17], v[150:153], v[210:213], v[2:17]
	ds_read_b64_tr_b16 v[224:225], v197 offset:0x1200
	ds_read_b64_tr_b16 v[226:227], v197 offset:0x1a00
	v_max3_f32 v164, v164, v88, v89
	v_max3_f32 v164, v164, v90, v91
	v_max3_f32 v164, v164, v92, v93
	v_max3_f32 v164, v164, v94, v95
	v_max3_f32 v164, v164, v96, v97
	s_waitcnt lgkmcnt(6)
	v_mfma_f32_32x32x16_bf16 v[2:17], v[154:157], v[228:231], v[2:17]
	ds_read_b64_tr_b16 v[228:229], v197 offset:0x2200
	ds_read_b64_tr_b16 v[230:231], v197 offset:0x2a00
	ds_read_b64_tr_b16 v[236:237], v197 offset:0x3200
	ds_read_b64_tr_b16 v[238:239], v197 offset:0x3a00
	s_waitcnt lgkmcnt(8)
	v_mfma_f32_32x32x16_bf16 v[2:17], v[216:219], v[232:235], v[2:17]
	s_waitcnt lgkmcnt(6)
	v_mfma_f32_32x32x16_bf16 v[50:65], v[146:149], v[220:223], v[50:65]
	v_max3_f32 v164, v164, v66, v67
	v_max3_f32 v164, v164, v68, v69
	v_max3_f32 v164, v164, v70, v71
	v_max3_f32 v164, v164, v72, v73
	v_max3_f32 v164, v164, v74, v75
	v_max3_f32 v164, v164, v76, v77
	v_max3_f32 v164, v164, v78, v79
	s_waitcnt lgkmcnt(4)
	v_mfma_f32_32x32x16_bf16 v[50:65], v[150:153], v[224:227], v[50:65]
	v_max3_f32 v164, v164, v80, v81
	v_mov_b32_e32 v165, v164
	s_nop 1
	v_permlane32_swap_b32_e32 v164, v165
	ds_read_b64_tr_b16 v[220:221], v197 offset:0x400
	v_max_f32_e32 v165, v165, v165
	v_max_f32_e32 v164, v164, v164
	s_waitcnt lgkmcnt(3)
	v_mfma_f32_32x32x16_bf16 v[50:65], v[154:157], v[228:231], v[50:65]
	ds_read_b64_tr_b16 v[222:223], v197 offset:0xc00
	v_max_f32_e32 v164, v164, v165
	v_max_f32_e32 v165, v202, v202
	ds_read_b64_tr_b16 v[224:225], v197 offset:0x1400
	v_max_f32_e32 v165, v165, v164
	ds_read_b64_tr_b16 v[226:227], v197 offset:0x1c00
	v_sub_f32_e32 v215, v164, v202
	s_waitcnt lgkmcnt(4)
	v_mfma_f32_32x32x16_bf16 v[50:65], v[216:219], v[236:239], v[50:65]
	v_sub_f32_e32 v164, v202, v165
	ds_read_b64_tr_b16 v[228:229], v197 offset:0x2400
	v_mul_f32_e32 v164, 0x3dd53b94, v164
	ds_read_b64_tr_b16 v[230:231], v197 offset:0x2c00
	v_exp_f32_e32 v164, v164
	ds_read_b64_tr_b16 v[232:233], v197 offset:0x3400
	v_cmp_ge_f32_e32 vcc, s77, v215
	ds_read_b64_tr_b16 v[234:235], v197 offset:0x3c00
	s_cmp_eq_u64 vcc, exec
	s_cselect_b64 s[4:5], -1, 0
	v_cndmask_b32_e64 v164, v164, 1.0, s[4:5]
	s_waitcnt lgkmcnt(6)
	v_mfma_f32_32x32x16_bf16 v[34:49], v[146:149], v[220:223], v[34:49]
	ds_read_b64_tr_b16 v[220:221], v197 offset:0x600
	ds_read_b64_tr_b16 v[222:223], v197 offset:0xe00
	s_waitcnt lgkmcnt(6)
	v_mfma_f32_32x32x16_bf16 v[34:49], v[150:153], v[224:227], v[34:49]
	ds_read_b64_tr_b16 v[224:225], v197 offset:0x1600
	ds_read_b64_tr_b16 v[226:227], v197 offset:0x1e00
	s_waitcnt lgkmcnt(6)
	v_mfma_f32_32x32x16_bf16 v[34:49], v[154:157], v[228:231], v[34:49]
	ds_read_b64_tr_b16 v[228:229], v197 offset:0x2600
	ds_read_b64_tr_b16 v[230:231], v197 offset:0x2e00
	ds_read_b64_tr_b16 v[236:237], v197 offset:0x3600
	ds_read_b64_tr_b16 v[238:239], v197 offset:0x3e00
	s_waitcnt lgkmcnt(8)
	v_mfma_f32_32x32x16_bf16 v[34:49], v[216:219], v[232:235], v[34:49]
	s_waitcnt lgkmcnt(6)
	v_mfma_f32_32x32x16_bf16 v[18:33], v[146:149], v[220:223], v[18:33]
	v_cmp_gt_f32_e32 vcc, 1.0, v164
	s_waitcnt lgkmcnt(4)
	v_mfma_f32_32x32x16_bf16 v[18:33], v[150:153], v[224:227], v[18:33]
	s_waitcnt lgkmcnt(2)
	v_mfma_f32_32x32x16_bf16 v[18:33], v[154:157], v[228:231], v[18:33]
	s_waitcnt lgkmcnt(0)
	v_mfma_f32_32x32x16_bf16 v[18:33], v[216:219], v[236:239], v[18:33]
	s_cbranch_vccz .LBB0_547
	s_and_saveexec_b64 s[0:1], s[2:3]
	ds_write_b32 v170, v164 offset:128
	s_or_b64 exec, exec, s[0:1]
	s_waitcnt lgkmcnt(0)
	ds_read_b128 v[146:149], v158 offset:224
	ds_read_b128 v[150:153], v158 offset:192
	ds_read_b128 v[154:157], v158 offset:160
	ds_read_b128 v[216:219], v158 offset:128
	s_waitcnt lgkmcnt(0)
	v_pk_mul_f32 v[16:17], v[16:17], v[148:149]
	v_pk_mul_f32 v[12:13], v[12:13], v[152:153]
	v_pk_mul_f32 v[8:9], v[8:9], v[156:157]
	v_pk_mul_f32 v[4:5], v[4:5], v[218:219]
	v_pk_mul_f32 v[14:15], v[14:15], v[146:147]
	v_pk_mul_f32 v[10:11], v[10:11], v[150:151]
	v_pk_mul_f32 v[6:7], v[6:7], v[154:155]
	v_pk_mul_f32 v[2:3], v[2:3], v[216:217]
	v_pk_mul_f32 v[64:65], v[64:65], v[148:149]
	v_pk_mul_f32 v[60:61], v[60:61], v[152:153]
	v_pk_mul_f32 v[56:57], v[56:57], v[156:157]
	v_pk_mul_f32 v[52:53], v[52:53], v[218:219]
	v_pk_mul_f32 v[62:63], v[62:63], v[146:147]
	v_pk_mul_f32 v[58:59], v[58:59], v[150:151]
	v_pk_mul_f32 v[54:55], v[54:55], v[154:155]
	v_pk_mul_f32 v[50:51], v[50:51], v[216:217]
	v_pk_mul_f32 v[48:49], v[48:49], v[148:149]
	v_pk_mul_f32 v[44:45], v[44:45], v[152:153]
	v_pk_mul_f32 v[40:41], v[40:41], v[156:157]
	v_pk_mul_f32 v[36:37], v[36:37], v[218:219]
	v_pk_mul_f32 v[46:47], v[46:47], v[146:147]
	v_pk_mul_f32 v[42:43], v[42:43], v[150:151]
	v_pk_mul_f32 v[38:39], v[38:39], v[154:155]
	v_pk_mul_f32 v[34:35], v[34:35], v[216:217]
	v_pk_mul_f32 v[32:33], v[32:33], v[148:149]
	v_pk_mul_f32 v[28:29], v[28:29], v[152:153]
	v_pk_mul_f32 v[24:25], v[24:25], v[156:157]
	v_pk_mul_f32 v[20:21], v[20:21], v[218:219]
	v_pk_mul_f32 v[30:31], v[30:31], v[146:147]
	v_pk_mul_f32 v[26:27], v[26:27], v[150:151]
	v_pk_mul_f32 v[22:23], v[22:23], v[154:155]
	v_pk_mul_f32 v[18:19], v[18:19], v[216:217]

.LBB0_549:
	v_cndmask_b32_e64 v165, v165, v202, s[4:5]
	v_mul_f32_e32 v154, 0xbdd53b94, v165
	v_fmamk_f32 v202, v69, 0x3dd53b94, v154
	v_fmamk_f32 v215, v70, 0x3dd53b94, v154
	v_fmamk_f32 v155, v66, 0x3dd53b94, v154
	v_fmamk_f32 v156, v67, 0x3dd53b94, v154
	v_fmamk_f32 v157, v68, 0x3dd53b94, v154
	v_fmamk_f32 v216, v71, 0x3dd53b94, v154
	v_fmamk_f32 v217, v72, 0x3dd53b94, v154
	v_fmamk_f32 v218, v73, 0x3dd53b94, v154
	ds_read_b128 v[66:69], v174 offset:32768
	ds_read_b128 v[70:73], v174 offset:40960
	ds_read_b128 v[146:149], v176 offset:32768
	ds_read_b128 v[150:153], v176 offset:40960
	v_fmamk_f32 v224, v82, 0x3dd53b94, v154
	v_fmamk_f32 v225, v83, 0x3dd53b94, v154
	v_fmamk_f32 v226, v84, 0x3dd53b94, v154
	v_fmamk_f32 v227, v85, 0x3dd53b94, v154
	v_fmamk_f32 v228, v86, 0x3dd53b94, v154
	v_fmamk_f32 v229, v87, 0x3dd53b94, v154
	v_fmamk_f32 v230, v88, 0x3dd53b94, v154
	v_fmamk_f32 v231, v89, 0x3dd53b94, v154
	v_fmamk_f32 v234, v90, 0x3dd53b94, v154
	v_fmamk_f32 v235, v91, 0x3dd53b94, v154
	v_fmamk_f32 v236, v92, 0x3dd53b94, v154
	v_fmamk_f32 v237, v93, 0x3dd53b94, v154
	v_fmamk_f32 v238, v94, 0x3dd53b94, v154
	v_fmamk_f32 v239, v95, 0x3dd53b94, v154
	v_fmamk_f32 v240, v96, 0x3dd53b94, v154
	v_fmamk_f32 v241, v97, 0x3dd53b94, v154
	s_waitcnt lgkmcnt(3)
	v_mfma_f32_32x32x16_bf16 v[82:97], v[66:69], v[142:145], 0
	v_fmamk_f32 v232, v79, 0x3dd53b94, v154
	v_fmamk_f32 v233, v80, 0x3dd53b94, v154
	v_fmamk_f32 v219, v74, 0x3dd53b94, v154
	v_fmamk_f32 v220, v75, 0x3dd53b94, v154
	v_fmamk_f32 v221, v76, 0x3dd53b94, v154
	v_fmamk_f32 v222, v77, 0x3dd53b94, v154
	v_fmamk_f32 v223, v78, 0x3dd53b94, v154
	v_fmac_f32_e32 v154, 0x3dd53b94, v81
	s_waitcnt lgkmcnt(2)
	v_mfma_f32_32x32x16_bf16 v[66:81], v[70:73], v[142:145], 0
	v_exp_f32_e32 v224, v224
	v_exp_f32_e32 v225, v225
	v_exp_f32_e32 v226, v226
	v_add_f32_e32 v245, 0, v224
	v_add_f32_e32 v245, v225, v245
	v_add_f32_e32 v245, v226, v245
	s_waitcnt lgkmcnt(1)
	v_mfma_f32_32x32x16_bf16 v[82:97], v[146:149], v[138:141], v[82:97]
	v_exp_f32_e32 v227, v227
	v_exp_f32_e32 v228, v228
	v_add_f32_e32 v245, v227, v245
	v_add_f32_e32 v245, v228, v245
	s_waitcnt lgkmcnt(0)
	v_mfma_f32_32x32x16_bf16 v[66:81], v[150:153], v[138:141], v[66:81]
	ds_read_b128 v[146:149], v178 offset:32768
	ds_read_b128 v[150:153], v178 offset:40960
	v_exp_f32_e32 v229, v229
	v_exp_f32_e32 v230, v230
	v_add_f32_e32 v245, v229, v245
	v_add_f32_e32 v245, v230, v245
	s_cmp_lg_u32 s98, 0
	s_cbranch_scc1 .Lattn_mla_nopf
	s_add_u32 s0, s38, s20
	s_addc_u32 s1, s39, s21
	s_add_u32 s100, s0, s42
	s_addc_u32 s101, s1, s43
	s_mov_b32 m0, s93
	v_lshl_add_u64 v[254:255], v[246:247], 0, s[100:101]
	global_load_lds_dwordx4 v[254:255], off
	s_add_u32 s100, s0, s46
	s_addc_u32 s101, s1, s47
	s_mov_b32 m0, s94
	v_lshl_add_u64 v[254:255], v[246:247], 0, s[100:101]
	global_load_lds_dwordx4 v[254:255], off
	s_add_u32 s100, s0, s44
	s_addc_u32 s101, s1, s45
	s_add_i32 s98, s89, s24
	s_mov_b32 m0, s98
	v_lshl_add_u64 v[254:255], v[248:249], 0, s[100:101]
	global_load_lds_dwordx4 v[254:255], off
	s_add_u32 s100, s0, s50
	s_addc_u32 s101, s1, s51
	s_add_i32 m0, s98, 0x2000
	v_lshl_add_u64 v[254:255], v[248:249], 0, s[100:101]
	global_load_lds_dwordx4 v[254:255], off
	s_add_u32 s0, s38, s88
	s_addc_u32 s1, s39, s87
	s_add_u32 s0, s0, s58
	s_addc_u32 s1, s1, s59
	s_mov_b32 m0, s95
	v_lshl_add_u64 v[254:255], v[250:251], 0, s[0:1]
	global_load_lds_dwordx4 v[254:255], off
.Lattn_mla_nopf:
	s_waitcnt lgkmcnt(1)
	v_mfma_f32_32x32x16_bf16 v[82:97], v[146:149], v[134:137], v[82:97]
	s_waitcnt lgkmcnt(0)
	v_mfma_f32_32x32x16_bf16 v[66:81], v[150:153], v[134:137], v[66:81]
	ds_read_b128 v[146:149], v180 offset:32768
	ds_read_b128 v[150:153], v180 offset:40960
	v_exp_f32_e32 v231, v231
	v_exp_f32_e32 v234, v234
	v_exp_f32_e32 v235, v235
	v_add_f32_e32 v245, v231, v245
	v_add_f32_e32 v245, v234, v245
	v_add_f32_e32 v245, v235, v245
	s_waitcnt lgkmcnt(1)
	v_mfma_f32_32x32x16_bf16 v[82:97], v[146:149], v[130:133], v[82:97]
	s_waitcnt lgkmcnt(0)
	v_mfma_f32_32x32x16_bf16 v[66:81], v[150:153], v[130:133], v[66:81]
	ds_read_b128 v[146:149], v182 offset:32768
	ds_read_b128 v[150:153], v182 offset:40960
	v_exp_f32_e32 v236, v236
	v_exp_f32_e32 v237, v237
	v_exp_f32_e32 v238, v238
	v_add_f32_e32 v245, v236, v245
	v_add_f32_e32 v245, v237, v245
	v_add_f32_e32 v245, v238, v245
	s_waitcnt lgkmcnt(1)
	v_mfma_f32_32x32x16_bf16 v[82:97], v[146:149], v[126:129], v[82:97]
	s_waitcnt lgkmcnt(0)
	v_mfma_f32_32x32x16_bf16 v[66:81], v[150:153], v[126:129], v[66:81]
	ds_read_b128 v[146:149], v186 offset:32768
	ds_read_b128 v[150:153], v186 offset:40960
	v_exp_f32_e32 v239, v239
	v_exp_f32_e32 v240, v240
	v_exp_f32_e32 v241, v241
	v_add_f32_e32 v245, v239, v245
	v_add_f32_e32 v245, v240, v245
	v_add_f32_e32 v245, v241, v245
	s_waitcnt lgkmcnt(1)
	v_mfma_f32_32x32x16_bf16 v[82:97], v[146:149], v[122:125], v[82:97]
	s_waitcnt lgkmcnt(0)
	v_mfma_f32_32x32x16_bf16 v[66:81], v[150:153], v[122:125], v[66:81]
	ds_read_b128 v[146:149], v188 offset:32768
	ds_read_b128 v[150:153], v188 offset:40960
	v_exp_f32_e32 v155, v155
	v_exp_f32_e32 v156, v156
	v_exp_f32_e32 v157, v157
	v_add_f32_e32 v245, v155, v245
	v_add_f32_e32 v245, v156, v245
	v_add_f32_e32 v245, v157, v245
	s_waitcnt lgkmcnt(1)
	v_mfma_f32_32x32x16_bf16 v[82:97], v[146:149], v[118:121], v[82:97]
	s_waitcnt lgkmcnt(0)
	v_mfma_f32_32x32x16_bf16 v[66:81], v[150:153], v[118:121], v[66:81]
	ds_read_b128 v[146:149], v190 offset:32768
	ds_read_b128 v[150:153], v190 offset:40960
	v_exp_f32_e32 v202, v202
	v_exp_f32_e32 v215, v215
	v_exp_f32_e32 v216, v216
	v_add_f32_e32 v245, v202, v245
	v_add_f32_e32 v245, v215, v245
	v_add_f32_e32 v245, v216, v245
	s_waitcnt lgkmcnt(1)
	v_mfma_f32_32x32x16_bf16 v[82:97], v[146:149], v[114:117], v[82:97]
	s_waitcnt lgkmcnt(0)
	v_mfma_f32_32x32x16_bf16 v[66:81], v[150:153], v[114:117], v[66:81]
	ds_read_b128 v[146:149], v192
	ds_read_b128 v[150:153], v192 offset:4096
	v_exp_f32_e32 v217, v217
	v_exp_f32_e32 v218, v218
	v_exp_f32_e32 v219, v219
	v_add_f32_e32 v245, v217, v245
	v_add_f32_e32 v245, v218, v245
	v_add_f32_e32 v245, v219, v245
	s_waitcnt lgkmcnt(1)
	v_mfma_f32_32x32x16_bf16 v[82:97], v[146:149], v[110:113], v[82:97]
	s_waitcnt lgkmcnt(0)
	v_mfma_f32_32x32x16_bf16 v[66:81], v[150:153], v[110:113], v[66:81]
	ds_read_b128 v[146:149], v194
	ds_read_b128 v[150:153], v194 offset:4096
	v_exp_f32_e32 v220, v220
	v_exp_f32_e32 v221, v221
	v_exp_f32_e32 v222, v222
	v_add_f32_e32 v245, v220, v245
	v_add_f32_e32 v245, v221, v245
	v_add_f32_e32 v245, v222, v245
	s_waitcnt lgkmcnt(1)
	v_mfma_f32_32x32x16_bf16 v[82:97], v[146:149], v[106:109], v[82:97]
	s_waitcnt lgkmcnt(0)
	v_mfma_f32_32x32x16_bf16 v[66:81], v[150:153], v[106:109], v[66:81]
	ds_read_b128 v[146:149], v196
	ds_read_b128 v[150:153], v196 offset:4096
	v_exp_f32_e32 v223, v223
	v_exp_f32_e32 v242, v232
	v_exp_f32_e32 v243, v233
	v_add_f32_e32 v245, v223, v245
	v_add_f32_e32 v245, v242, v245
	v_add_f32_e32 v245, v243, v245
	s_waitcnt lgkmcnt(1)
	v_mfma_f32_32x32x16_bf16 v[82:97], v[146:149], v[102:105], v[82:97]
	s_waitcnt lgkmcnt(0)
	v_mfma_f32_32x32x16_bf16 v[66:81], v[150:153], v[102:105], v[66:81]
	ds_read_b128 v[146:149], v199
	ds_read_b128 v[150:153], v199 offset:4096
	v_lshl_add_u32 v214, s23, 14, v200
	ds_read_b64_tr_b16 v[206:207], v214 offset:0
	ds_read_b64_tr_b16 v[208:209], v214 offset:0x800
	ds_read_b64_tr_b16 v[210:211], v214 offset:0x1000
	ds_read_b64_tr_b16 v[212:213], v214 offset:0x1800
	v_exp_f32_e32 v244, v154
	s_waitcnt lgkmcnt(5)
	v_mfma_f32_32x32x16_bf16 v[82:97], v[146:149], v[98:101], v[82:97]
	s_waitcnt lgkmcnt(4)
	v_mfma_f32_32x32x16_bf16 v[66:81], v[150:153], v[98:101], v[66:81]
	v_add_f32_e32 v232, v244, v245
	v_mov_b32_e32 v233, v232
	s_nop 1
	v_permlane32_swap_b32_e32 v232, v233
	v_cvt_pk_bf16_f32 v146, v224, v225
	v_cvt_pk_bf16_f32 v147, v226, v227
	v_cvt_pk_bf16_f32 v148, v228, v229
	v_cvt_pk_bf16_f32 v149, v230, v231
	v_cvt_pk_bf16_f32 v150, v234, v235
	v_cvt_pk_bf16_f32 v151, v236, v237
	v_cvt_pk_bf16_f32 v152, v238, v239
	v_cvt_pk_bf16_f32 v153, v240, v241
	v_cvt_pk_bf16_f32 v154, v155, v156
	v_cvt_pk_bf16_f32 v155, v157, v202
	v_cvt_pk_bf16_f32 v156, v215, v216
	v_cvt_pk_bf16_f32 v157, v217, v218
	v_cvt_pk_bf16_f32 v216, v219, v220
	v_cvt_pk_bf16_f32 v217, v221, v222
	v_cvt_pk_bf16_f32 v218, v223, v242
	v_cvt_pk_bf16_f32 v219, v243, v244
	s_nop 0
	v_permlane32_swap_b32_e32 v146, v148
	v_permlane32_swap_b32_e32 v147, v149
	v_permlane32_swap_b32_e32 v150, v152
	v_permlane32_swap_b32_e32 v151, v153
	v_permlane32_swap_b32_e32 v154, v156
	v_permlane32_swap_b32_e32 v155, v157
	v_permlane32_swap_b32_e32 v216, v218
	v_permlane32_swap_b32_e32 v217, v219
	ds_read_b64_tr_b16 v[228:229], v214 offset:0x2000
	ds_read_b64_tr_b16 v[230:231], v214 offset:0x2800
	ds_read_b64_tr_b16 v[234:235], v214 offset:0x3000
	ds_read_b64_tr_b16 v[236:237], v214 offset:0x3800
	s_nop 0
	s_waitcnt lgkmcnt(6)
	v_mfma_f32_32x32x16_bf16 v[2:17], v[146:149], v[206:209], v[2:17]
	ds_read_b64_tr_b16 v[220:221], v214 offset:0x200
	ds_read_b64_tr_b16 v[222:223], v214 offset:0xa00
	v_max_f32_e32 v202, v83, v83
	v_max_f32_e32 v215, v82, v82
	v_max_f32_e32 v202, v215, v202
	v_max3_f32 v202, v202, v84, v85
	v_max3_f32 v202, v202, v86, v87
	s_waitcnt lgkmcnt(6)
	v_mfma_f32_32x32x16_bf16 v[2:17], v[150:153], v[210:213], v[2:17]
	ds_read_b64_tr_b16 v[224:225], v214 offset:0x1200
	ds_read_b64_tr_b16 v[226:227], v214 offset:0x1a00
	v_max3_f32 v202, v202, v88, v89
	v_max3_f32 v202, v202, v90, v91
	v_max3_f32 v202, v202, v92, v93
	v_max3_f32 v202, v202, v94, v95
	v_max3_f32 v202, v202, v96, v97
	s_waitcnt lgkmcnt(6)
	v_mfma_f32_32x32x16_bf16 v[2:17], v[154:157], v[228:231], v[2:17]
	ds_read_b64_tr_b16 v[228:229], v214 offset:0x2200
	ds_read_b64_tr_b16 v[230:231], v214 offset:0x2a00
	ds_read_b64_tr_b16 v[238:239], v214 offset:0x3200
	ds_read_b64_tr_b16 v[240:241], v214 offset:0x3a00
	s_waitcnt lgkmcnt(8)
	v_mfma_f32_32x32x16_bf16 v[2:17], v[216:219], v[234:237], v[2:17]
	s_waitcnt lgkmcnt(6)
	v_mfma_f32_32x32x16_bf16 v[50:65], v[146:149], v[220:223], v[50:65]
	v_max3_f32 v202, v202, v66, v67
	v_max3_f32 v202, v202, v68, v69
	v_max3_f32 v202, v202, v70, v71
	v_max3_f32 v202, v202, v72, v73
	v_max3_f32 v202, v202, v74, v75
	v_max3_f32 v202, v202, v76, v77
	v_max3_f32 v202, v202, v78, v79
	s_waitcnt lgkmcnt(4)
	v_mfma_f32_32x32x16_bf16 v[50:65], v[150:153], v[224:227], v[50:65]
	v_max3_f32 v202, v202, v80, v81
	v_mov_b32_e32 v215, v202
	s_nop 1
	v_permlane32_swap_b32_e32 v202, v215
	v_max_f32_e32 v215, v215, v215
	v_max_f32_e32 v202, v202, v202
	v_max_f32_e32 v202, v202, v215
	v_max_f32_e32 v220, v165, v165
	v_sub_f32_e32 v215, v202, v165
	v_max_f32_e32 v202, v220, v202
	v_sub_f32_e32 v220, v165, v202
	v_mul_f32_e32 v220, 0x3dd53b94, v220
	s_waitcnt lgkmcnt(2)
	v_mfma_f32_32x32x16_bf16 v[50:65], v[154:157], v[228:231], v[50:65]
	v_exp_f32_e32 v220, v220
	v_cmp_ge_f32_e32 vcc, s77, v215
	s_cmp_eq_u64 vcc, exec
	s_cselect_b64 s[4:5], -1, 0
	v_cndmask_b32_e64 v215, v220, 1.0, s[4:5]
	ds_read_b64_tr_b16 v[220:221], v214 offset:0x400
	ds_read_b64_tr_b16 v[222:223], v214 offset:0xc00
	ds_read_b64_tr_b16 v[224:225], v214 offset:0x1400
	s_waitcnt lgkmcnt(3)
	v_mfma_f32_32x32x16_bf16 v[50:65], v[216:219], v[238:241], v[50:65]
	ds_read_b64_tr_b16 v[226:227], v214 offset:0x1c00
	ds_read_b64_tr_b16 v[228:229], v214 offset:0x2400
	ds_read_b64_tr_b16 v[230:231], v214 offset:0x2c00
	ds_read_b64_tr_b16 v[234:235], v214 offset:0x3400
	ds_read_b64_tr_b16 v[236:237], v214 offset:0x3c00
	s_waitcnt lgkmcnt(6)
	v_mfma_f32_32x32x16_bf16 v[34:49], v[146:149], v[220:223], v[34:49]
	ds_read_b64_tr_b16 v[220:221], v214 offset:0x600
	ds_read_b64_tr_b16 v[222:223], v214 offset:0xe00
	s_waitcnt lgkmcnt(6)
	v_mfma_f32_32x32x16_bf16 v[34:49], v[150:153], v[224:227], v[34:49]
	ds_read_b64_tr_b16 v[224:225], v214 offset:0x1600
	ds_read_b64_tr_b16 v[226:227], v214 offset:0x1e00
	s_waitcnt lgkmcnt(6)
	v_mfma_f32_32x32x16_bf16 v[34:49], v[154:157], v[228:231], v[34:49]
	ds_read_b64_tr_b16 v[228:229], v214 offset:0x2600
	ds_read_b64_tr_b16 v[230:231], v214 offset:0x2e00
	ds_read_b64_tr_b16 v[238:239], v214 offset:0x3600
	ds_read_b64_tr_b16 v[240:241], v214 offset:0x3e00
	s_waitcnt lgkmcnt(8)
	v_mfma_f32_32x32x16_bf16 v[34:49], v[216:219], v[234:237], v[34:49]
	s_waitcnt lgkmcnt(6)
	v_mfma_f32_32x32x16_bf16 v[18:33], v[146:149], v[220:223], v[18:33]
	v_cmp_gt_f32_e32 vcc, 1.0, v215
	s_waitcnt lgkmcnt(4)
	v_mfma_f32_32x32x16_bf16 v[18:33], v[150:153], v[224:227], v[18:33]
	s_waitcnt lgkmcnt(2)
	v_mfma_f32_32x32x16_bf16 v[18:33], v[154:157], v[228:231], v[18:33]
	s_waitcnt lgkmcnt(0)
	v_mfma_f32_32x32x16_bf16 v[18:33], v[216:219], v[238:241], v[18:33]
	s_cbranch_vccz .LBB0_553
	s_and_saveexec_b64 s[0:1], s[2:3]
	ds_write_b32 v170, v215 offset:128
	s_or_b64 exec, exec, s[0:1]
	s_waitcnt lgkmcnt(0)
	ds_read_b128 v[146:149], v158 offset:224
	ds_read_b128 v[150:153], v158 offset:192
	ds_read_b128 v[154:157], v158 offset:160
	ds_read_b128 v[216:219], v158 offset:128
	s_waitcnt lgkmcnt(0)
	v_pk_mul_f32 v[16:17], v[16:17], v[148:149]
	v_pk_mul_f32 v[12:13], v[12:13], v[152:153]
	v_pk_mul_f32 v[8:9], v[8:9], v[156:157]
	v_pk_mul_f32 v[4:5], v[4:5], v[218:219]
	v_pk_mul_f32 v[14:15], v[14:15], v[146:147]
	v_pk_mul_f32 v[10:11], v[10:11], v[150:151]
	v_pk_mul_f32 v[6:7], v[6:7], v[154:155]
	v_pk_mul_f32 v[2:3], v[2:3], v[216:217]
	v_pk_mul_f32 v[64:65], v[64:65], v[148:149]
	v_pk_mul_f32 v[60:61], v[60:61], v[152:153]
	v_pk_mul_f32 v[56:57], v[56:57], v[156:157]
	v_pk_mul_f32 v[52:53], v[52:53], v[218:219]
	v_pk_mul_f32 v[62:63], v[62:63], v[146:147]
	v_pk_mul_f32 v[58:59], v[58:59], v[150:151]
	v_pk_mul_f32 v[54:55], v[54:55], v[154:155]
	v_pk_mul_f32 v[50:51], v[50:51], v[216:217]
	v_pk_mul_f32 v[48:49], v[48:49], v[148:149]
	v_pk_mul_f32 v[44:45], v[44:45], v[152:153]
	v_pk_mul_f32 v[40:41], v[40:41], v[156:157]
	v_pk_mul_f32 v[36:37], v[36:37], v[218:219]
	v_pk_mul_f32 v[46:47], v[46:47], v[146:147]
	v_pk_mul_f32 v[42:43], v[42:43], v[150:151]
	v_pk_mul_f32 v[38:39], v[38:39], v[154:155]
	v_pk_mul_f32 v[34:35], v[34:35], v[216:217]
	v_pk_mul_f32 v[32:33], v[32:33], v[148:149]
	v_pk_mul_f32 v[28:29], v[28:29], v[152:153]
	v_pk_mul_f32 v[24:25], v[24:25], v[156:157]
	v_pk_mul_f32 v[20:21], v[20:21], v[218:219]
	v_pk_mul_f32 v[30:31], v[30:31], v[146:147]
	v_pk_mul_f32 v[26:27], v[26:27], v[150:151]
	v_pk_mul_f32 v[22:23], v[22:23], v[154:155]
	v_pk_mul_f32 v[18:19], v[18:19], v[216:217]
